# K-loop DMA rebalance also on G2/G3/G4 main loops
# baseline (speedup 1.0000x reference)
.LBB0_521:
	v_lshrrev_b32_e32 v20, 1, v14
	v_and_b32_e32 v20, 24, v20
	v_and_b32_e32 v15, 15, v14
	v_lshlrev_b32_e32 v21, 1, v20
	v_lshlrev_b32_e32 v14, 2, v14
	v_lshl_or_b32 v142, s46, 6, v15
	v_lshl_or_b32 v15, v15, 6, v21
	s_lshl_b32 s8, s46, 13
	v_and_b32_e32 v14, 32, v14
	v_readlane_b32 s50, v254, 32
	v_bitop3_b32 v21, v15, s8, v14 bitop3:0xde
	s_lshl_b32 s8, s41, 5
	v_mov_b32_e32 v135, v1
	v_readlane_b32 s51, v254, 33
	s_and_b32 s10, s8, 0x60
	s_add_i32 m0, s53, 0x18000
	v_lshl_add_u64 v[2:3], v[2:3], 0, s[26:27]
	v_lshl_add_u64 v[16:17], s[50:51], 0, v[134:135]
	v_mov_b32_e32 v133, v1
	s_lshl_b32 s8, s10, 7
	s_waitcnt vmcnt(2)
	s_barrier
	global_load_lds_dwordx4 v[2:3], off
	v_lshl_add_u64 v[2:3], v[4:5], 0, s[26:27]
	s_add_i32 m0, s53, 0x1a000
	s_add_i32 s63, s53, 0x8000
	s_add_i32 s64, s53, 0xa000
	v_lshl_add_u64 v[18:19], s[50:51], 0, v[132:133]
	v_bitop3_b32 v143, v15, s8, v14 bitop3:0xde
	global_load_lds_dwordx4 v[2:3], off
	v_lshl_add_u64 v[2:3], v[16:17], 0, s[26:27]
	s_mov_b32 m0, s63
	s_add_u32 s8, s56, 0xb0080
	global_load_lds_dwordx4 v[2:3], off
	v_lshl_add_u64 v[2:3], v[18:19], 0, s[26:27]
	s_mov_b32 m0, s64
	s_addc_u32 s9, s57, 0
	s_mov_b64 s[100:101], s[8:9]
	global_load_lds_dwordx4 v[2:3], off
	v_or_b32_e32 v144, s10, v20
	s_movk_i32 s10, 0xb00
	v_lshrrev_b32_e32 v3, 1, v11
	v_mul_lo_u32 v2, v10, s10
	s_mov_b32 s11, 0xb000
	v_mad_u64_u32 v[2:3], s[8:9], v3, s11, v[2:3]
	v_or_b32_e32 v2, v2, v12
	v_add_lshl_u32 v2, v2, v13, 1
	v_mov_b32_e32 v3, v1
	s_mov_b64 s[38:39], 0xb0080
	v_lshl_add_u64 v[136:137], v[2:3], 0, s[38:39]
	v_lshrrev_b32_e32 v3, 1, v6
	v_mul_lo_u32 v2, v7, s10
	v_mad_u64_u32 v[2:3], s[8:9], v3, s11, v[2:3]
	s_waitcnt vmcnt(4)
	v_or_b32_e32 v2, v2, v8
	s_cmpk_lt_u32 s40, 0x100
	v_add_lshl_u32 v2, v2, v9, 1
	v_mov_b32_e32 v3, v1
	v_readlane_b32 s8, v254, 38
	s_cselect_b64 s[46:47], -1, 0
	v_lshl_add_u64 v[138:139], v[2:3], 0, s[38:39]
	s_mov_b32 s65, 0
	v_add_u32_e32 v145, 0, v21
	v_readlane_b32 s68, v254, 31
	s_mov_b32 s69, s8
	s_barrier
	v_readlane_b32 s9, v254, 39
	s_branch .LBB0_524

.LBB0_535:
	s_add_u32 s56, s50, 0x100
	s_addc_u32 s57, s51, 0
	s_add_i32 s8, 0, 0x10000
	s_cmp_eq_u32 s74, 40
	s_cselect_b32 s59, s41, s57
	s_cselect_b32 s58, s40, s56
	v_add_u32_e32 v140, s8, v143
	s_cselect_b32 s55, s49, s73
	s_cselect_b32 s54, s48, s72
	s_add_i32 s10, 0, 0x14000
	ds_read_b128 v[146:149], v140
	ds_read_b128 v[150:153], v140 offset:1024
	ds_read_b128 v[154:157], v140 offset:2048
	ds_read_b128 v[158:161], v140 offset:3072
	v_add_u32_e32 v140, s10, v143
	ds_read_b128 v[162:165], v140
	ds_read_b128 v[166:169], v140 offset:1024
	ds_read_b128 v[170:173], v140 offset:2048
	ds_read_b128 v[174:177], v140 offset:3072
	v_lshl_add_u64 v[140:141], s[100:101], 0, v[0:1]
	s_add_i32 m0, s52, 0x1c000
	s_nop 0
	global_load_lds_dwordx4 v[140:141], off
	v_lshl_add_u64 v[140:141], s[100:101], 0, v[130:131]
	s_add_i32 m0, s52, 0x1e000
	s_nop 0
	global_load_lds_dwordx4 v[140:141], off
	v_lshl_add_u64 v[140:141], s[50:51], 0, v[136:137]
	s_add_i32 m0, s53, 0xc000
	ds_read_b128 v[178:181], v145
	ds_read_b128 v[182:185], v145 offset:1024
	ds_read_b128 v[224:227], v145 offset:2048
	ds_read_b128 v[228:231], v145 offset:3072
	ds_read_b128 v[232:235], v145 offset:4096
	ds_read_b128 v[236:239], v145 offset:5120
	ds_read_b128 v[240:243], v145 offset:6144
	ds_read_b128 v[244:247], v145 offset:7168
	global_load_lds_dwordx4 v[140:141], off
	v_lshl_add_u64 v[140:141], s[50:51], 0, v[138:139]
	s_add_i32 m0, s53, 0xe000
	s_nop 0
	global_load_lds_dwordx4 v[140:141], off
	s_waitcnt vmcnt(8)
	s_waitcnt lgkmcnt(0)
	s_barrier
	s_setprio 1
	s_waitcnt lgkmcnt(0)
	v_mfma_f32_16x16x32_bf16 v[126:129], v[146:149], v[178:181], v[126:129]
	v_mfma_f32_16x16x32_bf16 v[122:125], v[154:157], v[178:181], v[122:125]
	v_mfma_f32_16x16x32_bf16 v[110:113], v[146:149], v[224:227], v[110:113]
	v_mfma_f32_16x16x32_bf16 v[106:109], v[154:157], v[224:227], v[106:109]
	v_mfma_f32_16x16x32_bf16 v[94:97], v[146:149], v[232:235], v[94:97]
	v_mfma_f32_16x16x32_bf16 v[90:93], v[154:157], v[232:235], v[90:93]
	v_mfma_f32_16x16x32_bf16 v[78:81], v[146:149], v[240:243], v[78:81]
	v_mfma_f32_16x16x32_bf16 v[74:77], v[154:157], v[240:243], v[74:77]
	v_mfma_f32_16x16x32_bf16 v[126:129], v[150:153], v[182:185], v[126:129]
	v_mfma_f32_16x16x32_bf16 v[122:125], v[158:161], v[182:185], v[122:125]
	v_mfma_f32_16x16x32_bf16 v[110:113], v[150:153], v[228:231], v[110:113]
	v_mfma_f32_16x16x32_bf16 v[106:109], v[158:161], v[228:231], v[106:109]
	v_mfma_f32_16x16x32_bf16 v[94:97], v[150:153], v[236:239], v[94:97]
	v_mfma_f32_16x16x32_bf16 v[90:93], v[158:161], v[236:239], v[90:93]
	v_mfma_f32_16x16x32_bf16 v[78:81], v[150:153], v[244:247], v[78:81]
	v_mfma_f32_16x16x32_bf16 v[74:77], v[158:161], v[244:247], v[74:77]
	s_setprio 0
	s_setprio 1
	v_mfma_f32_16x16x32_bf16 v[118:121], v[162:165], v[178:181], v[118:121]
	v_mfma_f32_16x16x32_bf16 v[114:117], v[170:173], v[178:181], v[114:117]
	v_mfma_f32_16x16x32_bf16 v[102:105], v[162:165], v[224:227], v[102:105]
	v_mfma_f32_16x16x32_bf16 v[98:101], v[170:173], v[224:227], v[98:101]
	v_mfma_f32_16x16x32_bf16 v[86:89], v[162:165], v[232:235], v[86:89]
	v_mfma_f32_16x16x32_bf16 v[82:85], v[170:173], v[232:235], v[82:85]
	v_mfma_f32_16x16x32_bf16 v[70:73], v[162:165], v[240:243], v[70:73]
	v_mfma_f32_16x16x32_bf16 v[66:69], v[170:173], v[240:243], v[66:69]
	v_mfma_f32_16x16x32_bf16 v[118:121], v[166:169], v[182:185], v[118:121]
	v_mfma_f32_16x16x32_bf16 v[114:117], v[174:177], v[182:185], v[114:117]
	v_mfma_f32_16x16x32_bf16 v[102:105], v[166:169], v[228:231], v[102:105]
	v_mfma_f32_16x16x32_bf16 v[98:101], v[174:177], v[228:231], v[98:101]
	v_mfma_f32_16x16x32_bf16 v[86:89], v[166:169], v[236:239], v[86:89]
	v_mfma_f32_16x16x32_bf16 v[82:85], v[174:177], v[236:239], v[82:85]
	v_mfma_f32_16x16x32_bf16 v[70:73], v[166:169], v[244:247], v[70:73]
	v_mfma_f32_16x16x32_bf16 v[66:69], v[174:177], v[244:247], v[66:69]
	s_setprio 0
	s_barrier
	s_add_i32 s8, s8, s52
	v_lshl_add_u64 v[140:141], s[54:55], 0, v[0:1]
	s_mov_b32 m0, s8
	ds_read_b128 v[178:181], v145 offset:16384
	ds_read_b128 v[182:185], v145 offset:17408
	ds_read_b128 v[224:227], v145 offset:18432
	ds_read_b128 v[228:231], v145 offset:19456
	ds_read_b128 v[232:235], v145 offset:20480
	ds_read_b128 v[236:239], v145 offset:21504
	ds_read_b128 v[240:243], v145 offset:22528
	ds_read_b128 v[244:247], v145 offset:23552
	global_load_lds_dwordx4 v[140:141], off
	s_add_i32 m0, s8, 0x2000
	v_lshl_add_u64 v[186:187], s[54:55], 0, v[130:131]
	global_load_lds_dwordx4 v[186:187], off
	v_lshl_add_u64 v[248:249], s[58:59], 0, v[132:133]
	v_lshl_add_u64 v[202:203], s[58:59], 0, v[134:135]
	s_mov_b32 m0, s53
	s_nop 0
	global_load_lds_dwordx4 v[202:203], off
	s_mov_b32 m0, s60
	s_nop 0
	global_load_lds_dwordx4 v[248:249], off
	s_waitcnt vmcnt(6)
	s_waitcnt lgkmcnt(0)
	s_barrier
	s_setprio 1
	s_waitcnt lgkmcnt(0)
	v_mfma_f32_16x16x32_bf16 v[62:65], v[146:149], v[178:181], v[62:65]
	v_mfma_f32_16x16x32_bf16 v[58:61], v[154:157], v[178:181], v[58:61]
	v_mfma_f32_16x16x32_bf16 v[46:49], v[146:149], v[224:227], v[46:49]
	v_mfma_f32_16x16x32_bf16 v[42:45], v[154:157], v[224:227], v[42:45]
	v_mfma_f32_16x16x32_bf16 v[30:33], v[146:149], v[232:235], v[30:33]
	v_mfma_f32_16x16x32_bf16 v[26:29], v[154:157], v[232:235], v[26:29]
	v_mfma_f32_16x16x32_bf16 v[14:17], v[146:149], v[240:243], v[14:17]
	v_mfma_f32_16x16x32_bf16 v[10:13], v[154:157], v[240:243], v[10:13]
	v_mfma_f32_16x16x32_bf16 v[62:65], v[150:153], v[182:185], v[62:65]
	v_mfma_f32_16x16x32_bf16 v[58:61], v[158:161], v[182:185], v[58:61]
	v_mfma_f32_16x16x32_bf16 v[46:49], v[150:153], v[228:231], v[46:49]
	v_mfma_f32_16x16x32_bf16 v[42:45], v[158:161], v[228:231], v[42:45]
	v_mfma_f32_16x16x32_bf16 v[30:33], v[150:153], v[236:239], v[30:33]
	v_mfma_f32_16x16x32_bf16 v[26:29], v[158:161], v[236:239], v[26:29]
	v_mfma_f32_16x16x32_bf16 v[14:17], v[150:153], v[244:247], v[14:17]
	v_mfma_f32_16x16x32_bf16 v[10:13], v[158:161], v[244:247], v[10:13]
	s_setprio 0
	s_setprio 1
	v_mfma_f32_16x16x32_bf16 v[54:57], v[162:165], v[178:181], v[54:57]
	v_mfma_f32_16x16x32_bf16 v[50:53], v[170:173], v[178:181], v[50:53]
	v_mfma_f32_16x16x32_bf16 v[38:41], v[162:165], v[224:227], v[38:41]
	v_mfma_f32_16x16x32_bf16 v[34:37], v[170:173], v[224:227], v[34:37]
	v_mfma_f32_16x16x32_bf16 v[22:25], v[162:165], v[232:235], v[22:25]
	v_mfma_f32_16x16x32_bf16 v[18:21], v[170:173], v[232:235], v[18:21]
	v_mfma_f32_16x16x32_bf16 v[6:9], v[162:165], v[240:243], v[6:9]
	v_mfma_f32_16x16x32_bf16 v[2:5], v[170:173], v[240:243], v[2:5]
	v_mfma_f32_16x16x32_bf16 v[54:57], v[166:169], v[182:185], v[54:57]
	v_mfma_f32_16x16x32_bf16 v[50:53], v[174:177], v[182:185], v[50:53]
	v_mfma_f32_16x16x32_bf16 v[38:41], v[166:169], v[228:231], v[38:41]
	v_mfma_f32_16x16x32_bf16 v[34:37], v[174:177], v[228:231], v[34:37]
	v_mfma_f32_16x16x32_bf16 v[22:25], v[166:169], v[236:239], v[22:25]
	v_mfma_f32_16x16x32_bf16 v[18:21], v[174:177], v[236:239], v[18:21]
	v_mfma_f32_16x16x32_bf16 v[6:9], v[166:169], v[244:247], v[6:9]
	v_mfma_f32_16x16x32_bf16 v[2:5], v[174:177], v[244:247], v[2:5]
	s_setprio 0
	s_barrier
	s_add_i32 s10, 0, 0x18000
	s_add_i32 s11, 0, 0x1c000
	v_add_u32_e32 v158, s10, v143
	v_add_u32_e32 v174, s11, v143
	ds_read_b128 v[146:149], v158
	ds_read_b128 v[150:153], v158 offset:1024
	ds_read_b128 v[154:157], v158 offset:2048
	ds_read_b128 v[158:161], v158 offset:3072
	ds_read_b128 v[162:165], v174
	ds_read_b128 v[166:169], v174 offset:1024
	ds_read_b128 v[170:173], v174 offset:2048
	ds_read_b128 v[174:177], v174 offset:3072
	s_add_u32 s100, s54, 0xb0000
	s_addc_u32 s101, s55, 0
	v_lshl_add_u64 v[250:251], s[100:101], 0, v[0:1]
	s_add_i32 m0, s52, 0x14000
	s_nop 0
	global_load_lds_dwordx4 v[250:251], off
	v_lshl_add_u64 v[250:251], s[100:101], 0, v[130:131]
	s_add_i32 m0, s52, 0x16000
	s_nop 0
	global_load_lds_dwordx4 v[250:251], off
	s_add_u32 s8, s58, 0xb0000
	s_addc_u32 s9, s59, 0
	s_mov_b32 m0, s61
	v_lshl_add_u64 v[250:251], s[8:9], 0, v[134:135]
	ds_read_b128 v[178:181], v145 offset:32768
	ds_read_b128 v[182:185], v145 offset:33792
	ds_read_b128 v[224:227], v145 offset:34816
	ds_read_b128 v[228:231], v145 offset:35840
	ds_read_b128 v[232:235], v145 offset:36864
	ds_read_b128 v[236:239], v145 offset:37888
	ds_read_b128 v[240:243], v145 offset:38912
	ds_read_b128 v[244:247], v145 offset:39936
	global_load_lds_dwordx4 v[250:251], off
	v_lshl_add_u64 v[250:251], s[8:9], 0, v[132:133]
	s_mov_b32 m0, s62
	s_nop 0
	global_load_lds_dwordx4 v[250:251], off
	s_waitcnt vmcnt(8)
	s_waitcnt lgkmcnt(0)
	s_barrier
	s_setprio 1
	s_waitcnt lgkmcnt(0)
	v_mfma_f32_16x16x32_bf16 v[126:129], v[146:149], v[178:181], v[126:129]
	v_mfma_f32_16x16x32_bf16 v[122:125], v[154:157], v[178:181], v[122:125]
	v_mfma_f32_16x16x32_bf16 v[110:113], v[146:149], v[224:227], v[110:113]
	v_mfma_f32_16x16x32_bf16 v[106:109], v[154:157], v[224:227], v[106:109]
	v_mfma_f32_16x16x32_bf16 v[94:97], v[146:149], v[232:235], v[94:97]
	v_mfma_f32_16x16x32_bf16 v[90:93], v[154:157], v[232:235], v[90:93]
	v_mfma_f32_16x16x32_bf16 v[78:81], v[146:149], v[240:243], v[78:81]
	v_mfma_f32_16x16x32_bf16 v[74:77], v[154:157], v[240:243], v[74:77]
	v_mfma_f32_16x16x32_bf16 v[126:129], v[150:153], v[182:185], v[126:129]
	v_mfma_f32_16x16x32_bf16 v[122:125], v[158:161], v[182:185], v[122:125]
	v_mfma_f32_16x16x32_bf16 v[110:113], v[150:153], v[228:231], v[110:113]
	v_mfma_f32_16x16x32_bf16 v[106:109], v[158:161], v[228:231], v[106:109]
	v_mfma_f32_16x16x32_bf16 v[94:97], v[150:153], v[236:239], v[94:97]
	v_mfma_f32_16x16x32_bf16 v[90:93], v[158:161], v[236:239], v[90:93]
	v_mfma_f32_16x16x32_bf16 v[78:81], v[150:153], v[244:247], v[78:81]
	v_mfma_f32_16x16x32_bf16 v[74:77], v[158:161], v[244:247], v[74:77]
	s_setprio 0
	s_setprio 1
	v_mfma_f32_16x16x32_bf16 v[118:121], v[162:165], v[178:181], v[118:121]
	v_mfma_f32_16x16x32_bf16 v[114:117], v[170:173], v[178:181], v[114:117]
	v_mfma_f32_16x16x32_bf16 v[102:105], v[162:165], v[224:227], v[102:105]
	v_mfma_f32_16x16x32_bf16 v[98:101], v[170:173], v[224:227], v[98:101]
	v_mfma_f32_16x16x32_bf16 v[86:89], v[162:165], v[232:235], v[86:89]
	v_mfma_f32_16x16x32_bf16 v[82:85], v[170:173], v[232:235], v[82:85]
	v_mfma_f32_16x16x32_bf16 v[70:73], v[162:165], v[240:243], v[70:73]
	v_mfma_f32_16x16x32_bf16 v[66:69], v[170:173], v[240:243], v[66:69]
	v_mfma_f32_16x16x32_bf16 v[118:121], v[166:169], v[182:185], v[118:121]
	v_mfma_f32_16x16x32_bf16 v[114:117], v[174:177], v[182:185], v[114:117]
	v_mfma_f32_16x16x32_bf16 v[102:105], v[166:169], v[228:231], v[102:105]
	v_mfma_f32_16x16x32_bf16 v[98:101], v[174:177], v[228:231], v[98:101]
	v_mfma_f32_16x16x32_bf16 v[86:89], v[166:169], v[236:239], v[86:89]
	v_mfma_f32_16x16x32_bf16 v[82:85], v[174:177], v[236:239], v[82:85]
	v_mfma_f32_16x16x32_bf16 v[70:73], v[166:169], v[244:247], v[70:73]
	v_mfma_f32_16x16x32_bf16 v[66:69], v[174:177], v[244:247], v[66:69]
	s_setprio 0
	s_barrier
	s_add_i32 s8, s10, s52
	v_lshl_add_u64 v[140:141], v[140:141], 0, s[26:27]
	s_mov_b32 m0, s8
	ds_read_b128 v[178:181], v145 offset:49152
	ds_read_b128 v[182:185], v145 offset:50176
	ds_read_b128 v[224:227], v145 offset:51200
	ds_read_b128 v[228:231], v145 offset:52224
	ds_read_b128 v[232:235], v145 offset:53248
	ds_read_b128 v[236:239], v145 offset:54272
	ds_read_b128 v[240:243], v145 offset:55296
	ds_read_b128 v[244:247], v145 offset:56320
	global_load_lds_dwordx4 v[140:141], off
	s_add_i32 m0, s8, 0x2000
	s_add_u32 s100, s54, 0xb0080
	s_addc_u32 s101, s55, 0
	v_lshl_add_u64 v[140:141], v[186:187], 0, s[26:27]
	global_load_lds_dwordx4 v[140:141], off
	v_lshl_add_u64 v[140:141], v[202:203], 0, s[26:27]
	s_mov_b32 m0, s63
	s_nop 0
	global_load_lds_dwordx4 v[140:141], off
	v_lshl_add_u64 v[140:141], v[248:249], 0, s[26:27]
	s_mov_b32 m0, s64
	s_nop 0
	global_load_lds_dwordx4 v[140:141], off
	s_waitcnt vmcnt(6)
	s_waitcnt lgkmcnt(0)
	s_barrier
	s_setprio 1
	s_waitcnt lgkmcnt(0)
	v_mfma_f32_16x16x32_bf16 v[62:65], v[146:149], v[178:181], v[62:65]
	v_mfma_f32_16x16x32_bf16 v[58:61], v[154:157], v[178:181], v[58:61]
	v_mfma_f32_16x16x32_bf16 v[46:49], v[146:149], v[224:227], v[46:49]
	v_mfma_f32_16x16x32_bf16 v[42:45], v[154:157], v[224:227], v[42:45]
	v_mfma_f32_16x16x32_bf16 v[30:33], v[146:149], v[232:235], v[30:33]
	v_mfma_f32_16x16x32_bf16 v[26:29], v[154:157], v[232:235], v[26:29]
	v_mfma_f32_16x16x32_bf16 v[14:17], v[146:149], v[240:243], v[14:17]
	v_mfma_f32_16x16x32_bf16 v[10:13], v[154:157], v[240:243], v[10:13]
	v_mfma_f32_16x16x32_bf16 v[62:65], v[150:153], v[182:185], v[62:65]
	v_mfma_f32_16x16x32_bf16 v[58:61], v[158:161], v[182:185], v[58:61]
	v_mfma_f32_16x16x32_bf16 v[46:49], v[150:153], v[228:231], v[46:49]
	v_mfma_f32_16x16x32_bf16 v[42:45], v[158:161], v[228:231], v[42:45]
	v_mfma_f32_16x16x32_bf16 v[30:33], v[150:153], v[236:239], v[30:33]
	v_mfma_f32_16x16x32_bf16 v[26:29], v[158:161], v[236:239], v[26:29]
	v_mfma_f32_16x16x32_bf16 v[14:17], v[150:153], v[244:247], v[14:17]
	v_mfma_f32_16x16x32_bf16 v[10:13], v[158:161], v[244:247], v[10:13]
	s_setprio 0
	s_setprio 1
	v_mfma_f32_16x16x32_bf16 v[54:57], v[162:165], v[178:181], v[54:57]
	v_mfma_f32_16x16x32_bf16 v[50:53], v[170:173], v[178:181], v[50:53]
	v_mfma_f32_16x16x32_bf16 v[38:41], v[162:165], v[224:227], v[38:41]
	v_mfma_f32_16x16x32_bf16 v[34:37], v[170:173], v[224:227], v[34:37]
	v_mfma_f32_16x16x32_bf16 v[22:25], v[162:165], v[232:235], v[22:25]
	v_mfma_f32_16x16x32_bf16 v[18:21], v[170:173], v[232:235], v[18:21]
	v_mfma_f32_16x16x32_bf16 v[6:9], v[162:165], v[240:243], v[6:9]
	v_mfma_f32_16x16x32_bf16 v[2:5], v[170:173], v[240:243], v[2:5]
	v_mfma_f32_16x16x32_bf16 v[54:57], v[166:169], v[182:185], v[54:57]
	v_mfma_f32_16x16x32_bf16 v[50:53], v[174:177], v[182:185], v[50:53]
	v_mfma_f32_16x16x32_bf16 v[38:41], v[166:169], v[228:231], v[38:41]
	v_mfma_f32_16x16x32_bf16 v[34:37], v[174:177], v[228:231], v[34:37]
	v_mfma_f32_16x16x32_bf16 v[22:25], v[166:169], v[236:239], v[22:25]
	v_mfma_f32_16x16x32_bf16 v[18:21], v[174:177], v[236:239], v[18:21]
	v_mfma_f32_16x16x32_bf16 v[6:9], v[166:169], v[244:247], v[6:9]
	v_mfma_f32_16x16x32_bf16 v[2:5], v[174:177], v[244:247], v[2:5]
	s_setprio 0
	s_barrier
	s_add_i32 s74, s74, 2
	s_add_u32 s72, s72, 0x100
	s_addc_u32 s73, s73, 0
	s_cmp_gt_u32 s74, 41
	s_mov_b64 s[50:51], s[56:57]
	s_cbranch_scc0 .LBB0_535
	s_and_b64 vcc, exec, s[46:47]
	s_cbranch_vccz .LBB0_538
	s_barrier

.LBB0_727:
	s_and_b32 s54, s5, 3
	s_add_i32 m0, s73, 0x18000
	v_lshl_add_u64 v[8:9], v[8:9], 0, s[26:27]
	s_lshl_b32 s28, s64, 6
	s_lshl_b32 s5, s38, 13
	s_lshl_b32 s55, s54, 5
	s_lshl_b32 s10, s54, 12
	s_waitcnt vmcnt(2)
	s_barrier
	global_load_lds_dwordx4 v[8:9], off
	v_lshl_add_u64 v[6:7], v[6:7], 0, s[26:27]
	s_add_i32 m0, s73, 0x1a000
	s_add_i32 s52, s73, 0x8000
	s_add_i32 s53, s73, 0xa000
	global_load_lds_dwordx4 v[6:7], off
	v_lshl_add_u64 v[2:3], v[2:3], 0, s[26:27]
	s_mov_b32 m0, s52
	s_add_u32 s8, s42, 0x40080
	global_load_lds_dwordx4 v[2:3], off
	v_lshl_add_u64 v[2:3], v[4:5], 0, s[26:27]
	s_mov_b32 m0, s53
	s_addc_u32 s9, s43, 0
	s_mov_b64 s[100:101], s[8:9]
	global_load_lds_dwordx4 v[2:3], off
	s_cmpk_lt_u32 s4, 0x100
	s_cselect_b64 s[56:57], -1, 0
	s_lshl_b32 s4, s64, 26
	s_waitcnt lgkmcnt(0)
	s_add_u32 s4, s0, s4
	v_lshrrev_b32_e32 v3, 1, v0
	v_writelane_b32 v255, s4, 12
	s_addc_u32 s4, s1, 0
	v_and_b32_e32 v144, 24, v3
	v_writelane_b32 v255, s4, 14
	s_add_i32 s4, s75, -1
	v_and_b32_e32 v2, 15, v0
	v_lshlrev_b32_e32 v3, 1, v144
	v_lshlrev_b32_e32 v0, 2, v0
	v_writelane_b32 v255, s4, 16
	v_lshl_or_b32 v145, s38, 6, v2
	v_lshl_or_b32 v2, v2, 6, v3
	v_and_b32_e32 v0, 32, v0
	v_readlane_b32 s8, v255, 1
	v_bitop3_b32 v3, v2, s5, v0 bitop3:0xde
	v_bitop3_b32 v164, v2, s10, v0 bitop3:0xde
	v_readlane_b32 s9, v255, 2
	s_add_u32 s4, s8, 0x11620000
	v_lshlrev_b32_e32 v0, 14, v10
	s_addc_u32 s5, s9, 0
	v_and_b32_e32 v0, 0xffff8000, v0
	v_writelane_b32 v255, s4, 17
	v_lshl_add_u32 v0, v11, 11, v0
	v_and_b32_e32 v2, 1, v10
	v_writelane_b32 v255, s5, 18
	v_lshl_or_b32 v0, v2, 6, v0
	v_writelane_b32 v255, s64, 19
	s_lshl_b32 s4, s64, 19
	v_lshl_add_u32 v146, v12, 1, v0
	v_lshlrev_b32_e32 v0, 14, v13
	v_writelane_b32 v255, s65, 20
	s_add_u32 s0, s0, s4
	v_and_b32_e32 v0, 0xffff8000, v0
	s_waitcnt vmcnt(4)
	v_writelane_b32 v255, s0, 21
	s_addc_u32 s0, s1, 0
	v_lshl_add_u32 v0, v14, 11, v0
	v_and_b32_e32 v2, 1, v13
	s_add_u32 s84, s8, 0x11800000
	v_lshl_or_b32 v0, v2, 6, v0
	v_writelane_b32 v255, s0, 23
	s_addc_u32 s85, s9, 0
	v_mov_b32_e32 v147, v1
	v_lshl_add_u32 v148, v15, 1, v0
	v_mov_b32_e32 v149, v1
	s_mov_b32 s4, 0
	v_add_u32_e32 v165, 0, v3
	s_lshl_b64 s[60:61], s[28:29], 2
	s_barrier
	s_branch .LBB0_730

.LBB0_737:
	s_add_u32 s8, s40, 0xfffc0080
	s_addc_u32 s9, s41, -1
	s_add_i32 s10, 0, 0x10000
	s_cmp_eq_u32 s59, 12
	s_cselect_b32 s45, s0, s9
	s_cselect_b32 s44, s1, s8
	v_add_u32_e32 v0, s10, v164
	s_cselect_b32 s43, s5, s58
	s_cselect_b32 s42, s25, s28
	s_add_i32 s11, 0, 0x14000
	ds_read_b128 v[130:133], v0
	ds_read_b128 v[150:153], v0 offset:1024
	ds_read_b128 v[154:157], v0 offset:2048
	ds_read_b128 v[158:161], v0 offset:3072
	v_add_u32_e32 v0, s11, v164
	ds_read_b128 v[166:169], v0
	ds_read_b128 v[170:173], v0 offset:1024
	ds_read_b128 v[174:177], v0 offset:2048
	ds_read_b128 v[178:181], v0 offset:3072
	v_lshl_add_u64 v[134:135], s[100:101], 0, v[138:139]
	s_add_i32 m0, s94, 0x1c000
	s_nop 0
	global_load_lds_dwordx4 v[134:135], off
	v_lshl_add_u64 v[134:135], s[100:101], 0, v[142:143]
	s_add_i32 m0, s94, 0x1e000
	s_nop 0
	global_load_lds_dwordx4 v[134:135], off
	v_lshl_add_u64 v[134:135], s[40:41], 0, v[146:147]
	s_add_i32 m0, s73, 0xc000
	ds_read_b128 v[182:185], v165
	ds_read_b128 v[224:227], v165 offset:1024
	ds_read_b128 v[228:231], v165 offset:2048
	ds_read_b128 v[232:235], v165 offset:3072
	ds_read_b128 v[236:239], v165 offset:4096
	ds_read_b128 v[240:243], v165 offset:5120
	ds_read_b128 v[244:247], v165 offset:6144
	ds_read_b128 v[248:251], v165 offset:7168
	global_load_lds_dwordx4 v[134:135], off
	v_lshl_add_u64 v[134:135], s[40:41], 0, v[148:149]
	s_add_i32 m0, s73, 0xe000
	s_nop 0
	global_load_lds_dwordx4 v[134:135], off
	s_waitcnt vmcnt(8)
	s_waitcnt lgkmcnt(0)
	s_barrier
	s_setprio 1
	s_waitcnt lgkmcnt(0)
	v_mfma_f32_16x16x32_bf16 v[126:129], v[130:133], v[182:185], v[126:129]
	v_mfma_f32_16x16x32_bf16 v[122:125], v[154:157], v[182:185], v[122:125]
	v_mfma_f32_16x16x32_bf16 v[118:121], v[130:133], v[228:231], v[118:121]
	v_mfma_f32_16x16x32_bf16 v[114:117], v[154:157], v[228:231], v[114:117]
	v_mfma_f32_16x16x32_bf16 v[106:109], v[130:133], v[236:239], v[106:109]
	v_mfma_f32_16x16x32_bf16 v[98:101], v[154:157], v[236:239], v[98:101]
	v_mfma_f32_16x16x32_bf16 v[90:93], v[130:133], v[244:247], v[90:93]
	v_mfma_f32_16x16x32_bf16 v[82:85], v[154:157], v[244:247], v[82:85]
	v_mfma_f32_16x16x32_bf16 v[126:129], v[150:153], v[224:227], v[126:129]
	v_mfma_f32_16x16x32_bf16 v[122:125], v[158:161], v[224:227], v[122:125]
	v_mfma_f32_16x16x32_bf16 v[118:121], v[150:153], v[232:235], v[118:121]
	v_mfma_f32_16x16x32_bf16 v[114:117], v[158:161], v[232:235], v[114:117]
	v_mfma_f32_16x16x32_bf16 v[106:109], v[150:153], v[240:243], v[106:109]
	v_mfma_f32_16x16x32_bf16 v[98:101], v[158:161], v[240:243], v[98:101]
	v_mfma_f32_16x16x32_bf16 v[90:93], v[150:153], v[248:251], v[90:93]
	v_mfma_f32_16x16x32_bf16 v[82:85], v[158:161], v[248:251], v[82:85]
	s_setprio 0
	s_setprio 1
	v_mfma_f32_16x16x32_bf16 v[110:113], v[166:169], v[182:185], v[110:113]
	v_mfma_f32_16x16x32_bf16 v[102:105], v[174:177], v[182:185], v[102:105]
	v_mfma_f32_16x16x32_bf16 v[94:97], v[166:169], v[228:231], v[94:97]
	v_mfma_f32_16x16x32_bf16 v[86:89], v[174:177], v[228:231], v[86:89]
	v_mfma_f32_16x16x32_bf16 v[78:81], v[166:169], v[236:239], v[78:81]
	v_mfma_f32_16x16x32_bf16 v[74:77], v[174:177], v[236:239], v[74:77]
	v_mfma_f32_16x16x32_bf16 v[70:73], v[166:169], v[244:247], v[70:73]
	v_mfma_f32_16x16x32_bf16 v[66:69], v[174:177], v[244:247], v[66:69]
	v_mfma_f32_16x16x32_bf16 v[110:113], v[170:173], v[224:227], v[110:113]
	v_mfma_f32_16x16x32_bf16 v[102:105], v[178:181], v[224:227], v[102:105]
	v_mfma_f32_16x16x32_bf16 v[94:97], v[170:173], v[232:235], v[94:97]
	v_mfma_f32_16x16x32_bf16 v[86:89], v[178:181], v[232:235], v[86:89]
	v_mfma_f32_16x16x32_bf16 v[78:81], v[170:173], v[240:243], v[78:81]
	v_mfma_f32_16x16x32_bf16 v[74:77], v[178:181], v[240:243], v[74:77]
	v_mfma_f32_16x16x32_bf16 v[70:73], v[170:173], v[248:251], v[70:73]
	v_mfma_f32_16x16x32_bf16 v[66:69], v[178:181], v[248:251], v[66:69]
	s_setprio 0
	s_barrier
	s_add_i32 s8, s10, s94
	v_lshl_add_u64 v[134:135], s[42:43], 0, v[138:139]
	s_mov_b32 m0, s8
	ds_read_b128 v[182:185], v165 offset:16384
	ds_read_b128 v[224:227], v165 offset:17408
	ds_read_b128 v[228:231], v165 offset:18432
	ds_read_b128 v[232:235], v165 offset:19456
	ds_read_b128 v[236:239], v165 offset:20480
	ds_read_b128 v[240:243], v165 offset:21504
	ds_read_b128 v[244:247], v165 offset:22528
	ds_read_b128 v[248:251], v165 offset:23552
	global_load_lds_dwordx4 v[134:135], off
	s_add_i32 m0, s8, 0x2000
	v_lshl_add_u64 v[162:163], s[42:43], 0, v[142:143]
	global_load_lds_dwordx4 v[162:163], off
	v_lshl_add_u64 v[202:203], s[44:45], 0, v[140:141]
	v_lshl_add_u64 v[186:187], s[44:45], 0, v[136:137]
	s_mov_b32 m0, s73
	s_nop 0
	global_load_lds_dwordx4 v[186:187], off
	s_mov_b32 m0, s95
	s_nop 0
	global_load_lds_dwordx4 v[202:203], off
	s_waitcnt vmcnt(6)
	s_waitcnt lgkmcnt(0)
	s_barrier
	s_setprio 1
	s_waitcnt lgkmcnt(0)
	v_mfma_f32_16x16x32_bf16 v[62:65], v[130:133], v[182:185], v[62:65]
	v_mfma_f32_16x16x32_bf16 v[58:61], v[154:157], v[182:185], v[58:61]
	v_mfma_f32_16x16x32_bf16 v[54:57], v[130:133], v[228:231], v[54:57]
	v_mfma_f32_16x16x32_bf16 v[50:53], v[154:157], v[228:231], v[50:53]
	v_mfma_f32_16x16x32_bf16 v[42:45], v[130:133], v[236:239], v[42:45]
	v_mfma_f32_16x16x32_bf16 v[34:37], v[154:157], v[236:239], v[34:37]
	v_mfma_f32_16x16x32_bf16 v[26:29], v[130:133], v[244:247], v[26:29]
	v_mfma_f32_16x16x32_bf16 v[18:21], v[154:157], v[244:247], v[18:21]
	v_mfma_f32_16x16x32_bf16 v[62:65], v[150:153], v[224:227], v[62:65]
	v_mfma_f32_16x16x32_bf16 v[58:61], v[158:161], v[224:227], v[58:61]
	v_mfma_f32_16x16x32_bf16 v[54:57], v[150:153], v[232:235], v[54:57]
	v_mfma_f32_16x16x32_bf16 v[50:53], v[158:161], v[232:235], v[50:53]
	v_mfma_f32_16x16x32_bf16 v[42:45], v[150:153], v[240:243], v[42:45]
	v_mfma_f32_16x16x32_bf16 v[34:37], v[158:161], v[240:243], v[34:37]
	v_mfma_f32_16x16x32_bf16 v[26:29], v[150:153], v[248:251], v[26:29]
	v_mfma_f32_16x16x32_bf16 v[18:21], v[158:161], v[248:251], v[18:21]
	s_setprio 0
	s_setprio 1
	v_mfma_f32_16x16x32_bf16 v[46:49], v[166:169], v[182:185], v[46:49]
	v_mfma_f32_16x16x32_bf16 v[38:41], v[174:177], v[182:185], v[38:41]
	v_mfma_f32_16x16x32_bf16 v[30:33], v[166:169], v[228:231], v[30:33]
	v_mfma_f32_16x16x32_bf16 v[22:25], v[174:177], v[228:231], v[22:25]
	v_mfma_f32_16x16x32_bf16 v[14:17], v[166:169], v[236:239], v[14:17]
	v_mfma_f32_16x16x32_bf16 v[10:13], v[174:177], v[236:239], v[10:13]
	v_mfma_f32_16x16x32_bf16 v[6:9], v[166:169], v[244:247], v[6:9]
	v_mfma_f32_16x16x32_bf16 v[2:5], v[174:177], v[244:247], v[2:5]
	v_mfma_f32_16x16x32_bf16 v[46:49], v[170:173], v[224:227], v[46:49]
	v_mfma_f32_16x16x32_bf16 v[38:41], v[178:181], v[224:227], v[38:41]
	v_mfma_f32_16x16x32_bf16 v[30:33], v[170:173], v[232:235], v[30:33]
	v_mfma_f32_16x16x32_bf16 v[22:25], v[178:181], v[232:235], v[22:25]
	v_mfma_f32_16x16x32_bf16 v[14:17], v[170:173], v[240:243], v[14:17]
	v_mfma_f32_16x16x32_bf16 v[10:13], v[178:181], v[240:243], v[10:13]
	v_mfma_f32_16x16x32_bf16 v[6:9], v[170:173], v[248:251], v[6:9]
	v_mfma_f32_16x16x32_bf16 v[2:5], v[178:181], v[248:251], v[2:5]
	s_setprio 0
	s_barrier
	s_add_i32 s10, 0, 0x18000
	v_add_u32_e32 v0, s10, v164
	s_add_i32 s11, 0, 0x1c000
	ds_read_b128 v[130:133], v0
	ds_read_b128 v[150:153], v0 offset:1024
	ds_read_b128 v[154:157], v0 offset:2048
	ds_read_b128 v[158:161], v0 offset:3072
	v_add_u32_e32 v0, s11, v164
	ds_read_b128 v[166:169], v0
	ds_read_b128 v[170:173], v0 offset:1024
	ds_read_b128 v[174:177], v0 offset:2048
	ds_read_b128 v[178:181], v0 offset:3072
	s_add_u32 s100, s42, 0x40000
	s_addc_u32 s101, s43, 0
	v_lshl_add_u64 v[208:209], s[100:101], 0, v[138:139]
	s_add_i32 m0, s94, 0x14000
	s_nop 0
	global_load_lds_dwordx4 v[208:209], off
	v_lshl_add_u64 v[208:209], s[100:101], 0, v[142:143]
	s_add_i32 m0, s94, 0x16000
	s_nop 0
	global_load_lds_dwordx4 v[208:209], off
	s_add_u32 s8, s44, 0x40000
	s_addc_u32 s9, s45, 0
	s_mov_b32 m0, s96
	v_lshl_add_u64 v[208:209], s[8:9], 0, v[136:137]
	ds_read_b128 v[182:185], v165 offset:32768
	ds_read_b128 v[224:227], v165 offset:33792
	ds_read_b128 v[228:231], v165 offset:34816
	ds_read_b128 v[232:235], v165 offset:35840
	ds_read_b128 v[236:239], v165 offset:36864
	ds_read_b128 v[240:243], v165 offset:37888
	ds_read_b128 v[244:247], v165 offset:38912
	ds_read_b128 v[248:251], v165 offset:39936
	global_load_lds_dwordx4 v[208:209], off
	v_lshl_add_u64 v[208:209], s[8:9], 0, v[140:141]
	s_mov_b32 m0, s97
	s_nop 0
	global_load_lds_dwordx4 v[208:209], off
	s_waitcnt vmcnt(8)
	s_waitcnt lgkmcnt(0)
	s_barrier
	s_setprio 1
	s_waitcnt lgkmcnt(0)
	v_mfma_f32_16x16x32_bf16 v[126:129], v[130:133], v[182:185], v[126:129]
	v_mfma_f32_16x16x32_bf16 v[122:125], v[154:157], v[182:185], v[122:125]
	v_mfma_f32_16x16x32_bf16 v[118:121], v[130:133], v[228:231], v[118:121]
	v_mfma_f32_16x16x32_bf16 v[114:117], v[154:157], v[228:231], v[114:117]
	v_mfma_f32_16x16x32_bf16 v[106:109], v[130:133], v[236:239], v[106:109]
	v_mfma_f32_16x16x32_bf16 v[98:101], v[154:157], v[236:239], v[98:101]
	v_mfma_f32_16x16x32_bf16 v[90:93], v[130:133], v[244:247], v[90:93]
	v_mfma_f32_16x16x32_bf16 v[82:85], v[154:157], v[244:247], v[82:85]
	v_mfma_f32_16x16x32_bf16 v[126:129], v[150:153], v[224:227], v[126:129]
	v_mfma_f32_16x16x32_bf16 v[122:125], v[158:161], v[224:227], v[122:125]
	v_mfma_f32_16x16x32_bf16 v[118:121], v[150:153], v[232:235], v[118:121]
	v_mfma_f32_16x16x32_bf16 v[114:117], v[158:161], v[232:235], v[114:117]
	v_mfma_f32_16x16x32_bf16 v[106:109], v[150:153], v[240:243], v[106:109]
	v_mfma_f32_16x16x32_bf16 v[98:101], v[158:161], v[240:243], v[98:101]
	v_mfma_f32_16x16x32_bf16 v[90:93], v[150:153], v[248:251], v[90:93]
	v_mfma_f32_16x16x32_bf16 v[82:85], v[158:161], v[248:251], v[82:85]
	s_setprio 0
	s_setprio 1
	v_mfma_f32_16x16x32_bf16 v[110:113], v[166:169], v[182:185], v[110:113]
	v_mfma_f32_16x16x32_bf16 v[102:105], v[174:177], v[182:185], v[102:105]
	v_mfma_f32_16x16x32_bf16 v[94:97], v[166:169], v[228:231], v[94:97]
	v_mfma_f32_16x16x32_bf16 v[86:89], v[174:177], v[228:231], v[86:89]
	v_mfma_f32_16x16x32_bf16 v[78:81], v[166:169], v[236:239], v[78:81]
	v_mfma_f32_16x16x32_bf16 v[74:77], v[174:177], v[236:239], v[74:77]
	v_mfma_f32_16x16x32_bf16 v[70:73], v[166:169], v[244:247], v[70:73]
	v_mfma_f32_16x16x32_bf16 v[66:69], v[174:177], v[244:247], v[66:69]
	v_mfma_f32_16x16x32_bf16 v[110:113], v[170:173], v[224:227], v[110:113]
	v_mfma_f32_16x16x32_bf16 v[102:105], v[178:181], v[224:227], v[102:105]
	v_mfma_f32_16x16x32_bf16 v[94:97], v[170:173], v[232:235], v[94:97]
	v_mfma_f32_16x16x32_bf16 v[86:89], v[178:181], v[232:235], v[86:89]
	v_mfma_f32_16x16x32_bf16 v[78:81], v[170:173], v[240:243], v[78:81]
	v_mfma_f32_16x16x32_bf16 v[74:77], v[178:181], v[240:243], v[74:77]
	v_mfma_f32_16x16x32_bf16 v[70:73], v[170:173], v[248:251], v[70:73]
	v_mfma_f32_16x16x32_bf16 v[66:69], v[178:181], v[248:251], v[66:69]
	s_setprio 0
	s_barrier
	s_add_i32 s8, s10, s94
	v_lshl_add_u64 v[134:135], v[134:135], 0, s[26:27]
	s_mov_b32 m0, s8
	ds_read_b128 v[182:185], v165 offset:49152
	ds_read_b128 v[224:227], v165 offset:50176
	ds_read_b128 v[228:231], v165 offset:51200
	ds_read_b128 v[232:235], v165 offset:52224
	ds_read_b128 v[236:239], v165 offset:53248
	ds_read_b128 v[240:243], v165 offset:54272
	ds_read_b128 v[244:247], v165 offset:55296
	ds_read_b128 v[248:251], v165 offset:56320
	global_load_lds_dwordx4 v[134:135], off
	s_add_i32 m0, s8, 0x2000
	s_add_u32 s100, s42, 0x40080
	s_addc_u32 s101, s43, 0
	v_lshl_add_u64 v[134:135], v[162:163], 0, s[26:27]
	global_load_lds_dwordx4 v[134:135], off
	v_lshl_add_u64 v[134:135], v[186:187], 0, s[26:27]
	s_mov_b32 m0, s52
	s_nop 0
	global_load_lds_dwordx4 v[134:135], off
	v_lshl_add_u64 v[134:135], v[202:203], 0, s[26:27]
	s_mov_b32 m0, s53
	s_nop 0
	global_load_lds_dwordx4 v[134:135], off
	s_waitcnt vmcnt(6)
	s_waitcnt lgkmcnt(0)
	s_barrier
	s_setprio 1
	s_waitcnt lgkmcnt(0)
	v_mfma_f32_16x16x32_bf16 v[62:65], v[130:133], v[182:185], v[62:65]
	v_mfma_f32_16x16x32_bf16 v[58:61], v[154:157], v[182:185], v[58:61]
	v_mfma_f32_16x16x32_bf16 v[54:57], v[130:133], v[228:231], v[54:57]
	v_mfma_f32_16x16x32_bf16 v[50:53], v[154:157], v[228:231], v[50:53]
	v_mfma_f32_16x16x32_bf16 v[42:45], v[130:133], v[236:239], v[42:45]
	v_mfma_f32_16x16x32_bf16 v[34:37], v[154:157], v[236:239], v[34:37]
	v_mfma_f32_16x16x32_bf16 v[26:29], v[130:133], v[244:247], v[26:29]
	v_mfma_f32_16x16x32_bf16 v[18:21], v[154:157], v[244:247], v[18:21]
	v_mfma_f32_16x16x32_bf16 v[62:65], v[150:153], v[224:227], v[62:65]
	v_mfma_f32_16x16x32_bf16 v[58:61], v[158:161], v[224:227], v[58:61]
	v_mfma_f32_16x16x32_bf16 v[54:57], v[150:153], v[232:235], v[54:57]
	v_mfma_f32_16x16x32_bf16 v[50:53], v[158:161], v[232:235], v[50:53]
	v_mfma_f32_16x16x32_bf16 v[42:45], v[150:153], v[240:243], v[42:45]
	v_mfma_f32_16x16x32_bf16 v[34:37], v[158:161], v[240:243], v[34:37]
	v_mfma_f32_16x16x32_bf16 v[26:29], v[150:153], v[248:251], v[26:29]
	v_mfma_f32_16x16x32_bf16 v[18:21], v[158:161], v[248:251], v[18:21]
	s_setprio 0
	s_setprio 1
	v_mfma_f32_16x16x32_bf16 v[46:49], v[166:169], v[182:185], v[46:49]
	v_mfma_f32_16x16x32_bf16 v[38:41], v[174:177], v[182:185], v[38:41]
	v_mfma_f32_16x16x32_bf16 v[30:33], v[166:169], v[228:231], v[30:33]
	v_mfma_f32_16x16x32_bf16 v[22:25], v[174:177], v[228:231], v[22:25]
	v_mfma_f32_16x16x32_bf16 v[14:17], v[166:169], v[236:239], v[14:17]
	v_mfma_f32_16x16x32_bf16 v[10:13], v[174:177], v[236:239], v[10:13]
	v_mfma_f32_16x16x32_bf16 v[6:9], v[166:169], v[244:247], v[6:9]
	v_mfma_f32_16x16x32_bf16 v[2:5], v[174:177], v[244:247], v[2:5]
	v_mfma_f32_16x16x32_bf16 v[46:49], v[170:173], v[224:227], v[46:49]
	v_mfma_f32_16x16x32_bf16 v[38:41], v[178:181], v[224:227], v[38:41]
	v_mfma_f32_16x16x32_bf16 v[30:33], v[170:173], v[232:235], v[30:33]
	v_mfma_f32_16x16x32_bf16 v[22:25], v[178:181], v[232:235], v[22:25]
	v_mfma_f32_16x16x32_bf16 v[14:17], v[170:173], v[240:243], v[14:17]
	v_mfma_f32_16x16x32_bf16 v[10:13], v[178:181], v[240:243], v[10:13]
	v_mfma_f32_16x16x32_bf16 v[6:9], v[170:173], v[248:251], v[6:9]
	v_mfma_f32_16x16x32_bf16 v[2:5], v[178:181], v[248:251], v[2:5]
	s_setprio 0
	s_barrier
	s_add_i32 s59, s59, 2
	s_add_u32 s40, s40, 0x100
	s_addc_u32 s41, s41, 0
	s_add_u32 s28, s28, 0x100
	s_addc_u32 s58, s58, 0
	s_cmp_gt_u32 s59, 13
	s_cbranch_scc0 .LBB0_737
	s_and_b64 vcc, exec, s[56:57]
	s_cbranch_vccz .LBB0_740
	s_barrier

.LBB0_1528:
	v_lshrrev_b32_e32 v18, 1, v8
	v_and_b32_e32 v18, 24, v18
	v_and_b32_e32 v9, 15, v8
	v_lshlrev_b32_e32 v19, 1, v18
	v_lshlrev_b32_e32 v8, 2, v8
	v_lshl_or_b32 v142, s42, 6, v9
	v_lshl_or_b32 v9, v9, 6, v19
	s_lshl_b32 s8, s42, 13
	v_and_b32_e32 v8, 32, v8
	v_bitop3_b32 v19, v9, s8, v8 bitop3:0xde
	s_lshl_b32 s8, s39, 5
	s_and_b32 s10, s8, 0x60
	v_lshl_add_u64 v[10:11], s[54:55], 0, v[0:1]
	s_waitcnt lgkmcnt(0)
	v_mov_b32_e32 v131, v1
	v_readlane_b32 s52, v254, 40
	s_lshl_b32 s8, s10, 7
	v_lshl_add_u64 v[12:13], s[54:55], 0, v[130:131]
	v_mov_b32_e32 v135, v1
	v_readlane_b32 s53, v254, 41
	v_bitop3_b32 v143, v9, s8, v8 bitop3:0xde
	s_add_i32 m0, s58, 0x18000
	v_lshl_add_u64 v[8:9], v[10:11], 0, s[26:27]
	v_lshl_add_u64 v[14:15], s[52:53], 0, v[134:135]
	v_mov_b32_e32 v133, v1
	s_waitcnt vmcnt(2)
	s_barrier
	global_load_lds_dwordx4 v[8:9], off
	v_lshl_add_u64 v[8:9], v[12:13], 0, s[26:27]
	s_add_i32 m0, s58, 0x1a000
	s_add_i32 s62, s58, 0x8000
	s_add_i32 s63, s58, 0xa000
	v_lshl_add_u64 v[16:17], s[52:53], 0, v[132:133]
	global_load_lds_dwordx4 v[8:9], off
	v_lshl_add_u64 v[8:9], v[14:15], 0, s[26:27]
	s_mov_b32 m0, s62
	s_add_u32 s8, s54, 0x40080
	global_load_lds_dwordx4 v[8:9], off
	v_lshl_add_u64 v[8:9], v[16:17], 0, s[26:27]
	s_mov_b32 m0, s63
	s_addc_u32 s9, s55, 0
	s_mov_b64 s[100:101], s[8:9]
	global_load_lds_dwordx4 v[8:9], off
	s_cmpk_lt_u32 s38, 0x100
	v_lshlrev_b32_e32 v8, 14, v6
	v_and_b32_e32 v8, 0xffff8000, v8
	v_lshl_add_u32 v5, v5, 11, v8
	v_and_b32_e32 v6, 1, v6
	v_lshl_or_b32 v5, v6, 6, v5
	v_lshl_add_u32 v136, v7, 1, v5
	v_lshlrev_b32_e32 v5, 14, v2
	v_and_b32_e32 v5, 0xffff8000, v5
	s_waitcnt vmcnt(4)
	v_lshl_add_u32 v3, v3, 11, v5
	v_and_b32_e32 v2, 1, v2
	v_lshl_or_b32 v2, v2, 6, v3
	v_readlane_b32 s8, v254, 38
	s_cselect_b64 s[42:43], -1, 0
	v_or_b32_e32 v144, s10, v18
	v_mov_b32_e32 v137, v1
	v_lshl_add_u32 v138, v4, 1, v2
	v_mov_b32_e32 v139, v1
	s_mov_b32 s64, 0
	v_add_u32_e32 v145, 0, v19
	v_readlane_b32 s65, v254, 31
	s_mov_b32 s66, s8
	s_barrier
	v_readlane_b32 s9, v254, 39
	s_branch .LBB0_1531

.LBB0_1538:
	s_add_u32 s8, s52, 0xfffc0080
	s_addc_u32 s9, s53, -1
	s_add_i32 s10, 0, 0x10000
	s_cmp_eq_u32 s73, 12
	s_cselect_b32 s57, s47, s9
	s_cselect_b32 s56, s67, s8
	v_add_u32_e32 v140, s10, v143
	s_cselect_b32 s55, s45, s72
	s_cselect_b32 s54, s68, s69
	s_add_i32 s11, 0, 0x14000
	ds_read_b128 v[146:149], v140
	ds_read_b128 v[150:153], v140 offset:1024
	ds_read_b128 v[154:157], v140 offset:2048
	ds_read_b128 v[158:161], v140 offset:3072
	v_add_u32_e32 v140, s11, v143
	ds_read_b128 v[162:165], v140
	ds_read_b128 v[166:169], v140 offset:1024
	ds_read_b128 v[170:173], v140 offset:2048
	ds_read_b128 v[174:177], v140 offset:3072
	v_lshl_add_u64 v[140:141], s[100:101], 0, v[0:1]
	s_add_i32 m0, s28, 0x1c000
	s_nop 0
	global_load_lds_dwordx4 v[140:141], off
	v_lshl_add_u64 v[140:141], s[100:101], 0, v[130:131]
	s_add_i32 m0, s28, 0x1e000
	s_nop 0
	global_load_lds_dwordx4 v[140:141], off
	v_lshl_add_u64 v[140:141], s[52:53], 0, v[136:137]
	s_add_i32 m0, s58, 0xc000
	ds_read_b128 v[178:181], v145
	ds_read_b128 v[182:185], v145 offset:1024
	ds_read_b128 v[224:227], v145 offset:2048
	ds_read_b128 v[228:231], v145 offset:3072
	ds_read_b128 v[232:235], v145 offset:4096
	ds_read_b128 v[236:239], v145 offset:5120
	ds_read_b128 v[240:243], v145 offset:6144
	ds_read_b128 v[244:247], v145 offset:7168
	global_load_lds_dwordx4 v[140:141], off
	v_lshl_add_u64 v[140:141], s[52:53], 0, v[138:139]
	s_add_i32 m0, s58, 0xe000
	s_nop 0
	global_load_lds_dwordx4 v[140:141], off
	s_waitcnt vmcnt(8)
	s_waitcnt lgkmcnt(0)
	s_barrier
	s_setprio 1
	s_waitcnt lgkmcnt(0)
	v_mfma_f32_16x16x32_bf16 v[126:129], v[146:149], v[178:181], v[126:129]
	v_mfma_f32_16x16x32_bf16 v[122:125], v[154:157], v[178:181], v[122:125]
	v_mfma_f32_16x16x32_bf16 v[110:113], v[146:149], v[224:227], v[110:113]
	v_mfma_f32_16x16x32_bf16 v[106:109], v[154:157], v[224:227], v[106:109]
	v_mfma_f32_16x16x32_bf16 v[102:105], v[146:149], v[232:235], v[102:105]
	v_mfma_f32_16x16x32_bf16 v[98:101], v[154:157], v[232:235], v[98:101]
	v_mfma_f32_16x16x32_bf16 v[78:81], v[146:149], v[240:243], v[78:81]
	v_mfma_f32_16x16x32_bf16 v[74:77], v[154:157], v[240:243], v[74:77]
	v_mfma_f32_16x16x32_bf16 v[126:129], v[150:153], v[182:185], v[126:129]
	v_mfma_f32_16x16x32_bf16 v[122:125], v[158:161], v[182:185], v[122:125]
	v_mfma_f32_16x16x32_bf16 v[110:113], v[150:153], v[228:231], v[110:113]
	v_mfma_f32_16x16x32_bf16 v[106:109], v[158:161], v[228:231], v[106:109]
	v_mfma_f32_16x16x32_bf16 v[102:105], v[150:153], v[236:239], v[102:105]
	v_mfma_f32_16x16x32_bf16 v[98:101], v[158:161], v[236:239], v[98:101]
	v_mfma_f32_16x16x32_bf16 v[78:81], v[150:153], v[244:247], v[78:81]
	v_mfma_f32_16x16x32_bf16 v[74:77], v[158:161], v[244:247], v[74:77]
	s_setprio 0
	s_setprio 1
	v_mfma_f32_16x16x32_bf16 v[118:121], v[162:165], v[178:181], v[118:121]
	v_mfma_f32_16x16x32_bf16 v[114:117], v[170:173], v[178:181], v[114:117]
	v_mfma_f32_16x16x32_bf16 v[94:97], v[162:165], v[224:227], v[94:97]
	v_mfma_f32_16x16x32_bf16 v[90:93], v[170:173], v[224:227], v[90:93]
	v_mfma_f32_16x16x32_bf16 v[86:89], v[162:165], v[232:235], v[86:89]
	v_mfma_f32_16x16x32_bf16 v[82:85], v[170:173], v[232:235], v[82:85]
	v_mfma_f32_16x16x32_bf16 v[70:73], v[162:165], v[240:243], v[70:73]
	v_mfma_f32_16x16x32_bf16 v[66:69], v[170:173], v[240:243], v[66:69]
	v_mfma_f32_16x16x32_bf16 v[118:121], v[166:169], v[182:185], v[118:121]
	v_mfma_f32_16x16x32_bf16 v[114:117], v[174:177], v[182:185], v[114:117]
	v_mfma_f32_16x16x32_bf16 v[94:97], v[166:169], v[228:231], v[94:97]
	v_mfma_f32_16x16x32_bf16 v[90:93], v[174:177], v[228:231], v[90:93]
	v_mfma_f32_16x16x32_bf16 v[86:89], v[166:169], v[236:239], v[86:89]
	v_mfma_f32_16x16x32_bf16 v[82:85], v[174:177], v[236:239], v[82:85]
	v_mfma_f32_16x16x32_bf16 v[70:73], v[166:169], v[244:247], v[70:73]
	v_mfma_f32_16x16x32_bf16 v[66:69], v[174:177], v[244:247], v[66:69]
	s_setprio 0
	s_barrier
	s_add_i32 s8, s10, s28
	v_lshl_add_u64 v[140:141], s[54:55], 0, v[0:1]
	s_mov_b32 m0, s8
	ds_read_b128 v[178:181], v145 offset:16384
	ds_read_b128 v[182:185], v145 offset:17408
	ds_read_b128 v[224:227], v145 offset:18432
	ds_read_b128 v[228:231], v145 offset:19456
	ds_read_b128 v[232:235], v145 offset:20480
	ds_read_b128 v[236:239], v145 offset:21504
	ds_read_b128 v[240:243], v145 offset:22528
	ds_read_b128 v[244:247], v145 offset:23552
	global_load_lds_dwordx4 v[140:141], off
	s_add_i32 m0, s8, 0x2000
	v_lshl_add_u64 v[186:187], s[54:55], 0, v[130:131]
	global_load_lds_dwordx4 v[186:187], off
	v_lshl_add_u64 v[208:209], s[56:57], 0, v[132:133]
	v_lshl_add_u64 v[202:203], s[56:57], 0, v[134:135]
	s_mov_b32 m0, s58
	s_nop 0
	global_load_lds_dwordx4 v[202:203], off
	s_mov_b32 m0, s59
	s_nop 0
	global_load_lds_dwordx4 v[208:209], off
	s_waitcnt vmcnt(6)
	s_waitcnt lgkmcnt(0)
	s_barrier
	s_setprio 1
	s_waitcnt lgkmcnt(0)
	v_mfma_f32_16x16x32_bf16 v[62:65], v[146:149], v[178:181], v[62:65]
	v_mfma_f32_16x16x32_bf16 v[58:61], v[154:157], v[178:181], v[58:61]
	v_mfma_f32_16x16x32_bf16 v[46:49], v[146:149], v[224:227], v[46:49]
	v_mfma_f32_16x16x32_bf16 v[42:45], v[154:157], v[224:227], v[42:45]
	v_mfma_f32_16x16x32_bf16 v[30:33], v[146:149], v[232:235], v[30:33]
	v_mfma_f32_16x16x32_bf16 v[26:29], v[154:157], v[232:235], v[26:29]
	v_mfma_f32_16x16x32_bf16 v[14:17], v[146:149], v[240:243], v[14:17]
	v_mfma_f32_16x16x32_bf16 v[10:13], v[154:157], v[240:243], v[10:13]
	v_mfma_f32_16x16x32_bf16 v[62:65], v[150:153], v[182:185], v[62:65]
	v_mfma_f32_16x16x32_bf16 v[58:61], v[158:161], v[182:185], v[58:61]
	v_mfma_f32_16x16x32_bf16 v[46:49], v[150:153], v[228:231], v[46:49]
	v_mfma_f32_16x16x32_bf16 v[42:45], v[158:161], v[228:231], v[42:45]
	v_mfma_f32_16x16x32_bf16 v[30:33], v[150:153], v[236:239], v[30:33]
	v_mfma_f32_16x16x32_bf16 v[26:29], v[158:161], v[236:239], v[26:29]
	v_mfma_f32_16x16x32_bf16 v[14:17], v[150:153], v[244:247], v[14:17]
	v_mfma_f32_16x16x32_bf16 v[10:13], v[158:161], v[244:247], v[10:13]
	s_setprio 0
	s_setprio 1
	v_mfma_f32_16x16x32_bf16 v[54:57], v[162:165], v[178:181], v[54:57]
	v_mfma_f32_16x16x32_bf16 v[50:53], v[170:173], v[178:181], v[50:53]
	v_mfma_f32_16x16x32_bf16 v[38:41], v[162:165], v[224:227], v[38:41]
	v_mfma_f32_16x16x32_bf16 v[34:37], v[170:173], v[224:227], v[34:37]
	v_mfma_f32_16x16x32_bf16 v[22:25], v[162:165], v[232:235], v[22:25]
	v_mfma_f32_16x16x32_bf16 v[18:21], v[170:173], v[232:235], v[18:21]
	v_mfma_f32_16x16x32_bf16 v[6:9], v[162:165], v[240:243], v[6:9]
	v_mfma_f32_16x16x32_bf16 v[2:5], v[170:173], v[240:243], v[2:5]
	v_mfma_f32_16x16x32_bf16 v[54:57], v[166:169], v[182:185], v[54:57]
	v_mfma_f32_16x16x32_bf16 v[50:53], v[174:177], v[182:185], v[50:53]
	v_mfma_f32_16x16x32_bf16 v[38:41], v[166:169], v[228:231], v[38:41]
	v_mfma_f32_16x16x32_bf16 v[34:37], v[174:177], v[228:231], v[34:37]
	v_mfma_f32_16x16x32_bf16 v[22:25], v[166:169], v[236:239], v[22:25]
	v_mfma_f32_16x16x32_bf16 v[18:21], v[174:177], v[236:239], v[18:21]
	v_mfma_f32_16x16x32_bf16 v[6:9], v[166:169], v[244:247], v[6:9]
	v_mfma_f32_16x16x32_bf16 v[2:5], v[174:177], v[244:247], v[2:5]
	s_setprio 0
	s_barrier
	s_add_i32 s10, 0, 0x18000
	s_add_i32 s11, 0, 0x1c000
	v_add_u32_e32 v158, s10, v143
	v_add_u32_e32 v174, s11, v143
	ds_read_b128 v[146:149], v158
	ds_read_b128 v[150:153], v158 offset:1024
	ds_read_b128 v[154:157], v158 offset:2048
	ds_read_b128 v[158:161], v158 offset:3072
	ds_read_b128 v[162:165], v174
	ds_read_b128 v[166:169], v174 offset:1024
	ds_read_b128 v[170:173], v174 offset:2048
	ds_read_b128 v[174:177], v174 offset:3072
	s_add_u32 s100, s54, 0x40000
	s_addc_u32 s101, s55, 0
	v_lshl_add_u64 v[248:249], s[100:101], 0, v[0:1]
	s_add_i32 m0, s28, 0x14000
	s_nop 0
	global_load_lds_dwordx4 v[248:249], off
	v_lshl_add_u64 v[248:249], s[100:101], 0, v[130:131]
	s_add_i32 m0, s28, 0x16000
	s_nop 0
	global_load_lds_dwordx4 v[248:249], off
	s_add_u32 s8, s56, 0x40000
	s_addc_u32 s9, s57, 0
	s_mov_b32 m0, s60
	v_lshl_add_u64 v[248:249], s[8:9], 0, v[134:135]
	ds_read_b128 v[178:181], v145 offset:32768
	ds_read_b128 v[182:185], v145 offset:33792
	ds_read_b128 v[224:227], v145 offset:34816
	ds_read_b128 v[228:231], v145 offset:35840
	ds_read_b128 v[232:235], v145 offset:36864
	ds_read_b128 v[236:239], v145 offset:37888
	ds_read_b128 v[240:243], v145 offset:38912
	ds_read_b128 v[244:247], v145 offset:39936
	global_load_lds_dwordx4 v[248:249], off
	v_lshl_add_u64 v[248:249], s[8:9], 0, v[132:133]
	s_mov_b32 m0, s61
	s_nop 0
	global_load_lds_dwordx4 v[248:249], off
	s_waitcnt vmcnt(8)
	s_waitcnt lgkmcnt(0)
	s_barrier
	s_setprio 1
	s_waitcnt lgkmcnt(0)
	v_mfma_f32_16x16x32_bf16 v[126:129], v[146:149], v[178:181], v[126:129]
	v_mfma_f32_16x16x32_bf16 v[122:125], v[154:157], v[178:181], v[122:125]
	v_mfma_f32_16x16x32_bf16 v[110:113], v[146:149], v[224:227], v[110:113]
	v_mfma_f32_16x16x32_bf16 v[106:109], v[154:157], v[224:227], v[106:109]
	v_mfma_f32_16x16x32_bf16 v[102:105], v[146:149], v[232:235], v[102:105]
	v_mfma_f32_16x16x32_bf16 v[98:101], v[154:157], v[232:235], v[98:101]
	v_mfma_f32_16x16x32_bf16 v[78:81], v[146:149], v[240:243], v[78:81]
	v_mfma_f32_16x16x32_bf16 v[74:77], v[154:157], v[240:243], v[74:77]
	v_mfma_f32_16x16x32_bf16 v[126:129], v[150:153], v[182:185], v[126:129]
	v_mfma_f32_16x16x32_bf16 v[122:125], v[158:161], v[182:185], v[122:125]
	v_mfma_f32_16x16x32_bf16 v[110:113], v[150:153], v[228:231], v[110:113]
	v_mfma_f32_16x16x32_bf16 v[106:109], v[158:161], v[228:231], v[106:109]
	v_mfma_f32_16x16x32_bf16 v[102:105], v[150:153], v[236:239], v[102:105]
	v_mfma_f32_16x16x32_bf16 v[98:101], v[158:161], v[236:239], v[98:101]
	v_mfma_f32_16x16x32_bf16 v[78:81], v[150:153], v[244:247], v[78:81]
	v_mfma_f32_16x16x32_bf16 v[74:77], v[158:161], v[244:247], v[74:77]
	s_setprio 0
	s_setprio 1
	v_mfma_f32_16x16x32_bf16 v[118:121], v[162:165], v[178:181], v[118:121]
	v_mfma_f32_16x16x32_bf16 v[114:117], v[170:173], v[178:181], v[114:117]
	v_mfma_f32_16x16x32_bf16 v[94:97], v[162:165], v[224:227], v[94:97]
	v_mfma_f32_16x16x32_bf16 v[90:93], v[170:173], v[224:227], v[90:93]
	v_mfma_f32_16x16x32_bf16 v[86:89], v[162:165], v[232:235], v[86:89]
	v_mfma_f32_16x16x32_bf16 v[82:85], v[170:173], v[232:235], v[82:85]
	v_mfma_f32_16x16x32_bf16 v[70:73], v[162:165], v[240:243], v[70:73]
	v_mfma_f32_16x16x32_bf16 v[66:69], v[170:173], v[240:243], v[66:69]
	v_mfma_f32_16x16x32_bf16 v[118:121], v[166:169], v[182:185], v[118:121]
	v_mfma_f32_16x16x32_bf16 v[114:117], v[174:177], v[182:185], v[114:117]
	v_mfma_f32_16x16x32_bf16 v[94:97], v[166:169], v[228:231], v[94:97]
	v_mfma_f32_16x16x32_bf16 v[90:93], v[174:177], v[228:231], v[90:93]
	v_mfma_f32_16x16x32_bf16 v[86:89], v[166:169], v[236:239], v[86:89]
	v_mfma_f32_16x16x32_bf16 v[82:85], v[174:177], v[236:239], v[82:85]
	v_mfma_f32_16x16x32_bf16 v[70:73], v[166:169], v[244:247], v[70:73]
	v_mfma_f32_16x16x32_bf16 v[66:69], v[174:177], v[244:247], v[66:69]
	s_setprio 0
	s_barrier
	s_add_i32 s8, s10, s28
	v_lshl_add_u64 v[140:141], v[140:141], 0, s[26:27]
	s_mov_b32 m0, s8
	ds_read_b128 v[178:181], v145 offset:49152
	ds_read_b128 v[182:185], v145 offset:50176
	ds_read_b128 v[224:227], v145 offset:51200
	ds_read_b128 v[228:231], v145 offset:52224
	ds_read_b128 v[232:235], v145 offset:53248
	ds_read_b128 v[236:239], v145 offset:54272
	ds_read_b128 v[240:243], v145 offset:55296
	ds_read_b128 v[244:247], v145 offset:56320
	global_load_lds_dwordx4 v[140:141], off
	s_add_i32 m0, s8, 0x2000
	s_add_u32 s100, s54, 0x40080
	s_addc_u32 s101, s55, 0
	v_lshl_add_u64 v[140:141], v[186:187], 0, s[26:27]
	global_load_lds_dwordx4 v[140:141], off
	v_lshl_add_u64 v[140:141], v[202:203], 0, s[26:27]
	s_mov_b32 m0, s62
	s_nop 0
	global_load_lds_dwordx4 v[140:141], off
	v_lshl_add_u64 v[140:141], v[208:209], 0, s[26:27]
	s_mov_b32 m0, s63
	s_nop 0
	global_load_lds_dwordx4 v[140:141], off
	s_waitcnt vmcnt(6)
	s_waitcnt lgkmcnt(0)
	s_barrier
	s_setprio 1
	s_waitcnt lgkmcnt(0)
	v_mfma_f32_16x16x32_bf16 v[62:65], v[146:149], v[178:181], v[62:65]
	v_mfma_f32_16x16x32_bf16 v[58:61], v[154:157], v[178:181], v[58:61]
	v_mfma_f32_16x16x32_bf16 v[46:49], v[146:149], v[224:227], v[46:49]
	v_mfma_f32_16x16x32_bf16 v[42:45], v[154:157], v[224:227], v[42:45]
	v_mfma_f32_16x16x32_bf16 v[30:33], v[146:149], v[232:235], v[30:33]
	v_mfma_f32_16x16x32_bf16 v[26:29], v[154:157], v[232:235], v[26:29]
	v_mfma_f32_16x16x32_bf16 v[14:17], v[146:149], v[240:243], v[14:17]
	v_mfma_f32_16x16x32_bf16 v[10:13], v[154:157], v[240:243], v[10:13]
	v_mfma_f32_16x16x32_bf16 v[62:65], v[150:153], v[182:185], v[62:65]
	v_mfma_f32_16x16x32_bf16 v[58:61], v[158:161], v[182:185], v[58:61]
	v_mfma_f32_16x16x32_bf16 v[46:49], v[150:153], v[228:231], v[46:49]
	v_mfma_f32_16x16x32_bf16 v[42:45], v[158:161], v[228:231], v[42:45]
	v_mfma_f32_16x16x32_bf16 v[30:33], v[150:153], v[236:239], v[30:33]
	v_mfma_f32_16x16x32_bf16 v[26:29], v[158:161], v[236:239], v[26:29]
	v_mfma_f32_16x16x32_bf16 v[14:17], v[150:153], v[244:247], v[14:17]
	v_mfma_f32_16x16x32_bf16 v[10:13], v[158:161], v[244:247], v[10:13]
	s_setprio 0
	s_setprio 1
	v_mfma_f32_16x16x32_bf16 v[54:57], v[162:165], v[178:181], v[54:57]
	v_mfma_f32_16x16x32_bf16 v[50:53], v[170:173], v[178:181], v[50:53]
	v_mfma_f32_16x16x32_bf16 v[38:41], v[162:165], v[224:227], v[38:41]
	v_mfma_f32_16x16x32_bf16 v[34:37], v[170:173], v[224:227], v[34:37]
	v_mfma_f32_16x16x32_bf16 v[22:25], v[162:165], v[232:235], v[22:25]
	v_mfma_f32_16x16x32_bf16 v[18:21], v[170:173], v[232:235], v[18:21]
	v_mfma_f32_16x16x32_bf16 v[6:9], v[162:165], v[240:243], v[6:9]
	v_mfma_f32_16x16x32_bf16 v[2:5], v[170:173], v[240:243], v[2:5]
	v_mfma_f32_16x16x32_bf16 v[54:57], v[166:169], v[182:185], v[54:57]
	v_mfma_f32_16x16x32_bf16 v[50:53], v[174:177], v[182:185], v[50:53]
	v_mfma_f32_16x16x32_bf16 v[38:41], v[166:169], v[228:231], v[38:41]
	v_mfma_f32_16x16x32_bf16 v[34:37], v[174:177], v[228:231], v[34:37]
	v_mfma_f32_16x16x32_bf16 v[22:25], v[166:169], v[236:239], v[22:25]
	v_mfma_f32_16x16x32_bf16 v[18:21], v[174:177], v[236:239], v[18:21]
	v_mfma_f32_16x16x32_bf16 v[6:9], v[166:169], v[244:247], v[6:9]
	v_mfma_f32_16x16x32_bf16 v[2:5], v[174:177], v[244:247], v[2:5]
	s_setprio 0
	s_barrier
	s_add_i32 s73, s73, 2
	s_add_u32 s52, s52, 0x100
	s_addc_u32 s53, s53, 0
	s_add_u32 s69, s69, 0x100
	s_addc_u32 s72, s72, 0
	s_cmp_gt_u32 s73, 13
	s_cbranch_scc0 .LBB0_1538
	s_and_b64 vcc, exec, s[42:43]
	s_mov_b64 s[68:69], s[36:37]
	s_cbranch_vccz .LBB0_1541
	s_barrier
